# up K-loop: LDS-DMA addresses via SGPR base + 32-bit VGPR offset (saddr form), removing 16 64-bit VALU adds per loop iteration from the load segments
# speedup vs baseline: 1.0090x; 1.0004x over previous
.LBB0_389:
	s_ashr_i32 s29, s28, 31
	s_lshl_b64 s[4:5], s[28:29], 19
	s_add_u32 s30, s12, s4
	s_addc_u32 s31, s13, s5
	s_and_b64 s[4:5], s[40:41], exec
	s_cselect_b32 s29, s31, s43
	s_cselect_b32 vcc_lo, s30, s42
	s_ashr_i32 s37, s36, 31
	s_lshl_b64 s[4:5], s[36:37], 19
	s_add_u32 s34, s17, s4
	s_addc_u32 s35, s70, s5
	s_and_b64 s[4:5], s[40:41], exec
	s_cselect_b32 s37, s35, s39
	s_cselect_b32 vcc_hi, s34, s38
	s_add_u32 s59, s38, 0x100
	v_mov_b32_e32 v74, 0
	s_addc_u32 s72, s39, 0
	s_mov_b32 s73, -2
	s_add_u32 s38, s42, 0x100
	s_addc_u32 s39, s43, 0
	s_add_i32 s4, 0, 0x10000
	s_cmp_eq_u32 s73, 12
	s_cselect_b32 s69, s29, s39
	s_cselect_b32 s68, vcc_lo, s38
	s_cselect_b32 s67, s37, s72
	s_cselect_b32 s66, vcc_hi, s59
	s_add_i32 s6, 0, 0x14000
	v_add_u32_e32 v142, s4, v251
	v_add_u32_e32 v158, s6, v251
	ds_read_b128 v[130:133], v142
	ds_read_b128 v[134:137], v142 offset:1024
	ds_read_b128 v[138:141], v142 offset:2048
	ds_read_b128 v[142:145], v142 offset:3072
	ds_read_b128 v[146:149], v158
	ds_read_b128 v[150:153], v158 offset:1024
	ds_read_b128 v[154:157], v158 offset:2048
	ds_read_b128 v[158:161], v158 offset:3072
	s_add_i32 m0, s75, 0xc000
	ds_read_b128 v[162:165], v244
	ds_read_b128 v[166:169], v244 offset:1024
	ds_read_b128 v[170:173], v244 offset:2048
	ds_read_b128 v[174:177], v244 offset:3072
	ds_read_b128 v[178:181], v244 offset:4096
	ds_read_b128 v[182:185], v244 offset:5120
	ds_read_b128 v[186:189], v244 offset:6144
	ds_read_b128 v[190:193], v244 offset:7168
	global_load_lds_dwordx4 v228, s[42:43]
	s_add_i32 m0, s75, 0xe000
	s_nop 0
	global_load_lds_dwordx4 v230, s[42:43]
	s_waitcnt vmcnt(8)
	s_waitcnt lgkmcnt(0)
	s_barrier
	s_setprio 1
	s_waitcnt lgkmcnt(0)
	v_mfma_f32_16x16x32_bf16 v[114:117], v[130:133], v[162:165], 0
	v_mfma_f32_16x16x32_bf16 v[122:125], v[138:141], v[162:165], 0
	v_mfma_f32_16x16x32_bf16 v[118:121], v[130:133], v[170:173], 0
	v_mfma_f32_16x16x32_bf16 v[126:129], v[138:141], v[170:173], 0
	v_mfma_f32_16x16x32_bf16 v[54:57], v[130:133], v[178:181], 0
	v_mfma_f32_16x16x32_bf16 v[70:73], v[138:141], v[178:181], 0
	v_mfma_f32_16x16x32_bf16 v[50:53], v[130:133], v[186:189], 0
	v_mfma_f32_16x16x32_bf16 v[66:69], v[138:141], v[186:189], 0
	v_mfma_f32_16x16x32_bf16 v[114:117], v[134:137], v[166:169], v[114:117]
	v_mfma_f32_16x16x32_bf16 v[122:125], v[142:145], v[166:169], v[122:125]
	v_mfma_f32_16x16x32_bf16 v[118:121], v[134:137], v[174:177], v[118:121]
	v_mfma_f32_16x16x32_bf16 v[126:129], v[142:145], v[174:177], v[126:129]
	v_mfma_f32_16x16x32_bf16 v[54:57], v[134:137], v[182:185], v[54:57]
	v_mfma_f32_16x16x32_bf16 v[70:73], v[142:145], v[182:185], v[70:73]
	v_mfma_f32_16x16x32_bf16 v[50:53], v[134:137], v[190:193], v[50:53]
	v_mfma_f32_16x16x32_bf16 v[66:69], v[142:145], v[190:193], v[66:69]
	s_setprio 0
	s_setprio 1
	v_mfma_f32_16x16x32_bf16 v[106:109], v[146:149], v[162:165], 0
	v_mfma_f32_16x16x32_bf16 v[42:45], v[154:157], v[162:165], 0
	v_mfma_f32_16x16x32_bf16 v[110:113], v[146:149], v[170:173], 0
	v_mfma_f32_16x16x32_bf16 v[46:49], v[154:157], v[170:173], 0
	v_mfma_f32_16x16x32_bf16 v[30:33], v[146:149], v[178:181], 0
	v_mfma_f32_16x16x32_bf16 v[14:17], v[154:157], v[178:181], 0
	v_mfma_f32_16x16x32_bf16 v[26:29], v[146:149], v[186:189], 0
	v_mfma_f32_16x16x32_bf16 v[10:13], v[154:157], v[186:189], 0
	v_mfma_f32_16x16x32_bf16 v[106:109], v[150:153], v[166:169], v[106:109]
	v_mfma_f32_16x16x32_bf16 v[42:45], v[158:161], v[166:169], v[42:45]
	v_mfma_f32_16x16x32_bf16 v[110:113], v[150:153], v[174:177], v[110:113]
	v_mfma_f32_16x16x32_bf16 v[46:49], v[158:161], v[174:177], v[46:49]
	v_mfma_f32_16x16x32_bf16 v[30:33], v[150:153], v[182:185], v[30:33]
	v_mfma_f32_16x16x32_bf16 v[14:17], v[158:161], v[182:185], v[14:17]
	v_mfma_f32_16x16x32_bf16 v[26:29], v[150:153], v[190:193], v[26:29]
	s_barrier
	v_mfma_f32_16x16x32_bf16 v[10:13], v[158:161], v[190:193], v[10:13]
	s_setprio 0
	s_add_i32 s4, s4, s74
	s_mov_b32 m0, s4
	ds_read_b128 v[162:165], v244 offset:16384
	ds_read_b128 v[166:169], v244 offset:17408
	ds_read_b128 v[170:173], v244 offset:18432
	ds_read_b128 v[174:177], v244 offset:19456
	ds_read_b128 v[178:181], v244 offset:20480
	ds_read_b128 v[182:185], v244 offset:21504
	ds_read_b128 v[186:189], v244 offset:22528
	ds_read_b128 v[190:193], v244 offset:23552
	global_load_lds_dwordx4 v0, s[66:67]
	s_add_i32 m0, s4, 0x2000
	s_add_u32 s4, s66, 0x40000
	s_addc_u32 s5, s67, 0
	s_add_i32 s6, s6, s74
	global_load_lds_dwordx4 v224, s[66:67]
	s_mov_b32 m0, s6
	s_nop 0
	global_load_lds_dwordx4 v0, s[4:5]
	s_add_i32 m0, s6, 0x2000
	s_nop 0
	global_load_lds_dwordx4 v224, s[4:5]
	s_mov_b32 m0, s75
	s_nop 0
	global_load_lds_dwordx4 v226, s[68:69]
	s_mov_b32 m0, s76
	s_nop 0
	global_load_lds_dwordx4 v222, s[68:69]
	s_waitcnt vmcnt(8)
	s_waitcnt lgkmcnt(0)
	s_barrier
	s_setprio 1
	s_waitcnt lgkmcnt(0)
	v_mfma_f32_16x16x32_bf16 v[38:41], v[130:133], v[162:165], 0
	v_mfma_f32_16x16x32_bf16 v[62:65], v[138:141], v[162:165], 0
	v_mfma_f32_16x16x32_bf16 v[34:37], v[130:133], v[170:173], 0
	v_mfma_f32_16x16x32_bf16 v[58:61], v[138:141], v[170:173], 0
	v_mfma_f32_16x16x32_bf16 v[102:105], v[130:133], v[178:181], 0
	v_mfma_f32_16x16x32_bf16 v[98:101], v[138:141], v[178:181], 0
	v_mfma_f32_16x16x32_bf16 v[94:97], v[130:133], v[186:189], 0
	v_mfma_f32_16x16x32_bf16 v[90:93], v[138:141], v[186:189], 0
	v_mfma_f32_16x16x32_bf16 v[38:41], v[134:137], v[166:169], v[38:41]
	v_mfma_f32_16x16x32_bf16 v[62:65], v[142:145], v[166:169], v[62:65]
	v_mfma_f32_16x16x32_bf16 v[34:37], v[134:137], v[174:177], v[34:37]
	v_mfma_f32_16x16x32_bf16 v[58:61], v[142:145], v[174:177], v[58:61]
	v_mfma_f32_16x16x32_bf16 v[102:105], v[134:137], v[182:185], v[102:105]
	v_mfma_f32_16x16x32_bf16 v[98:101], v[142:145], v[182:185], v[98:101]
	v_mfma_f32_16x16x32_bf16 v[94:97], v[134:137], v[190:193], v[94:97]
	v_mfma_f32_16x16x32_bf16 v[90:93], v[142:145], v[190:193], v[90:93]
	s_setprio 0
	s_setprio 1
	v_mfma_f32_16x16x32_bf16 v[22:25], v[146:149], v[162:165], 0
	v_mfma_f32_16x16x32_bf16 v[6:9], v[154:157], v[162:165], 0
	v_mfma_f32_16x16x32_bf16 v[18:21], v[146:149], v[170:173], 0
	v_mfma_f32_16x16x32_bf16 v[2:5], v[154:157], v[170:173], 0
	v_mfma_f32_16x16x32_bf16 v[86:89], v[146:149], v[178:181], 0
	v_mfma_f32_16x16x32_bf16 v[82:85], v[154:157], v[178:181], 0
	v_mfma_f32_16x16x32_bf16 v[78:81], v[146:149], v[186:189], 0
	v_mfma_f32_16x16x32_bf16 v[74:77], v[154:157], v[186:189], 0
	v_mfma_f32_16x16x32_bf16 v[22:25], v[150:153], v[166:169], v[22:25]
	v_mfma_f32_16x16x32_bf16 v[6:9], v[158:161], v[166:169], v[6:9]
	v_mfma_f32_16x16x32_bf16 v[18:21], v[150:153], v[174:177], v[18:21]
	v_mfma_f32_16x16x32_bf16 v[2:5], v[158:161], v[174:177], v[2:5]
	v_mfma_f32_16x16x32_bf16 v[86:89], v[150:153], v[182:185], v[86:89]
	v_mfma_f32_16x16x32_bf16 v[82:85], v[158:161], v[182:185], v[82:85]
	v_mfma_f32_16x16x32_bf16 v[78:81], v[150:153], v[190:193], v[78:81]
	s_barrier
	v_mfma_f32_16x16x32_bf16 v[74:77], v[158:161], v[190:193], v[74:77]
	s_setprio 0
	s_add_i32 s6, 0, 0x18000
	s_add_i32 s7, 0, 0x1c000
	v_add_u32_e32 v142, s6, v251
	v_add_u32_e32 v158, s7, v251
	ds_read_b128 v[130:133], v142
	ds_read_b128 v[134:137], v142 offset:1024
	ds_read_b128 v[138:141], v142 offset:2048
	ds_read_b128 v[142:145], v142 offset:3072
	ds_read_b128 v[146:149], v158
	ds_read_b128 v[150:153], v158 offset:1024
	ds_read_b128 v[154:157], v158 offset:2048
	ds_read_b128 v[158:161], v158 offset:3072
	s_add_u32 s4, s68, 0x2000
	s_addc_u32 s5, s69, 0
	s_mov_b32 m0, s77
	ds_read_b128 v[162:165], v244 offset:32768
	ds_read_b128 v[166:169], v244 offset:33792
	ds_read_b128 v[170:173], v244 offset:34816
	ds_read_b128 v[174:177], v244 offset:35840
	ds_read_b128 v[178:181], v244 offset:36864
	ds_read_b128 v[182:185], v244 offset:37888
	ds_read_b128 v[186:189], v244 offset:38912
	ds_read_b128 v[190:193], v244 offset:39936
	global_load_lds_dwordx4 v226, s[4:5]
	s_mov_b32 m0, s78
	s_nop 0
	global_load_lds_dwordx4 v222, s[4:5]
	s_waitcnt vmcnt(8)
	s_waitcnt lgkmcnt(0)
	s_barrier
	s_setprio 1
	s_waitcnt lgkmcnt(0)
	v_mfma_f32_16x16x32_bf16 v[114:117], v[130:133], v[162:165], v[114:117]
	v_mfma_f32_16x16x32_bf16 v[122:125], v[138:141], v[162:165], v[122:125]
	v_mfma_f32_16x16x32_bf16 v[118:121], v[130:133], v[170:173], v[118:121]
	v_mfma_f32_16x16x32_bf16 v[126:129], v[138:141], v[170:173], v[126:129]
	v_mfma_f32_16x16x32_bf16 v[54:57], v[130:133], v[178:181], v[54:57]
	v_mfma_f32_16x16x32_bf16 v[70:73], v[138:141], v[178:181], v[70:73]
	v_mfma_f32_16x16x32_bf16 v[50:53], v[130:133], v[186:189], v[50:53]
	v_mfma_f32_16x16x32_bf16 v[66:69], v[138:141], v[186:189], v[66:69]
	v_mfma_f32_16x16x32_bf16 v[114:117], v[134:137], v[166:169], v[114:117]
	v_mfma_f32_16x16x32_bf16 v[122:125], v[142:145], v[166:169], v[122:125]
	v_mfma_f32_16x16x32_bf16 v[118:121], v[134:137], v[174:177], v[118:121]
	v_mfma_f32_16x16x32_bf16 v[126:129], v[142:145], v[174:177], v[126:129]
	v_mfma_f32_16x16x32_bf16 v[54:57], v[134:137], v[182:185], v[54:57]
	v_mfma_f32_16x16x32_bf16 v[70:73], v[142:145], v[182:185], v[70:73]
	v_mfma_f32_16x16x32_bf16 v[50:53], v[134:137], v[190:193], v[50:53]
	v_mfma_f32_16x16x32_bf16 v[66:69], v[142:145], v[190:193], v[66:69]
	s_setprio 0
	s_setprio 1
	v_mfma_f32_16x16x32_bf16 v[106:109], v[146:149], v[162:165], v[106:109]
	v_mfma_f32_16x16x32_bf16 v[42:45], v[154:157], v[162:165], v[42:45]
	v_mfma_f32_16x16x32_bf16 v[110:113], v[146:149], v[170:173], v[110:113]
	v_mfma_f32_16x16x32_bf16 v[46:49], v[154:157], v[170:173], v[46:49]
	v_mfma_f32_16x16x32_bf16 v[30:33], v[146:149], v[178:181], v[30:33]
	v_mfma_f32_16x16x32_bf16 v[14:17], v[154:157], v[178:181], v[14:17]
	v_mfma_f32_16x16x32_bf16 v[26:29], v[146:149], v[186:189], v[26:29]
	v_mfma_f32_16x16x32_bf16 v[10:13], v[154:157], v[186:189], v[10:13]
	v_mfma_f32_16x16x32_bf16 v[106:109], v[150:153], v[166:169], v[106:109]
	v_mfma_f32_16x16x32_bf16 v[42:45], v[158:161], v[166:169], v[42:45]
	v_mfma_f32_16x16x32_bf16 v[110:113], v[150:153], v[174:177], v[110:113]
	v_mfma_f32_16x16x32_bf16 v[46:49], v[158:161], v[174:177], v[46:49]
	v_mfma_f32_16x16x32_bf16 v[30:33], v[150:153], v[182:185], v[30:33]
	v_mfma_f32_16x16x32_bf16 v[14:17], v[158:161], v[182:185], v[14:17]
	v_mfma_f32_16x16x32_bf16 v[26:29], v[150:153], v[190:193], v[26:29]
	s_barrier
	v_mfma_f32_16x16x32_bf16 v[10:13], v[158:161], v[190:193], v[10:13]
	s_setprio 0
	s_add_i32 s4, s6, s74
	s_mov_b32 m0, s4
	ds_read_b128 v[162:165], v244 offset:49152
	ds_read_b128 v[166:169], v244 offset:50176
	ds_read_b128 v[170:173], v244 offset:51200
	ds_read_b128 v[174:177], v244 offset:52224
	ds_read_b128 v[178:181], v244 offset:53248
	ds_read_b128 v[182:185], v244 offset:54272
	ds_read_b128 v[186:189], v244 offset:55296
	ds_read_b128 v[190:193], v244 offset:56320
	s_add_u32 s100, s66, 0x80
	s_addc_u32 s101, s67, 0
	global_load_lds_dwordx4 v0, s[100:101]
	s_add_i32 m0, s4, 0x2000
	s_add_u32 s4, s66, 0x40080
	s_addc_u32 s5, s67, 0
	s_add_i32 s6, s7, s74
	global_load_lds_dwordx4 v224, s[100:101]
	s_mov_b32 m0, s6
	s_nop 0
	global_load_lds_dwordx4 v0, s[4:5]
	s_add_i32 m0, s6, 0x2000
	s_nop 0
	global_load_lds_dwordx4 v224, s[4:5]
	s_mov_b32 m0, s94
	s_nop 0
	s_add_u32 s100, s68, 0x80
	s_addc_u32 s101, s69, 0
	global_load_lds_dwordx4 v226, s[100:101]
	s_mov_b32 m0, s95
	s_nop 0
	global_load_lds_dwordx4 v222, s[100:101]
	s_waitcnt vmcnt(8)
	s_waitcnt lgkmcnt(0)
	s_barrier
	s_setprio 1
	s_waitcnt lgkmcnt(0)
	v_mfma_f32_16x16x32_bf16 v[38:41], v[130:133], v[162:165], v[38:41]
	v_mfma_f32_16x16x32_bf16 v[62:65], v[138:141], v[162:165], v[62:65]
	v_mfma_f32_16x16x32_bf16 v[34:37], v[130:133], v[170:173], v[34:37]
	v_mfma_f32_16x16x32_bf16 v[58:61], v[138:141], v[170:173], v[58:61]
	v_mfma_f32_16x16x32_bf16 v[102:105], v[130:133], v[178:181], v[102:105]
	v_mfma_f32_16x16x32_bf16 v[98:101], v[138:141], v[178:181], v[98:101]
	v_mfma_f32_16x16x32_bf16 v[94:97], v[130:133], v[186:189], v[94:97]
	v_mfma_f32_16x16x32_bf16 v[90:93], v[138:141], v[186:189], v[90:93]
	v_mfma_f32_16x16x32_bf16 v[38:41], v[134:137], v[166:169], v[38:41]
	v_mfma_f32_16x16x32_bf16 v[62:65], v[142:145], v[166:169], v[62:65]
	v_mfma_f32_16x16x32_bf16 v[34:37], v[134:137], v[174:177], v[34:37]
	v_mfma_f32_16x16x32_bf16 v[58:61], v[142:145], v[174:177], v[58:61]
	v_mfma_f32_16x16x32_bf16 v[102:105], v[134:137], v[182:185], v[102:105]
	v_mfma_f32_16x16x32_bf16 v[98:101], v[142:145], v[182:185], v[98:101]
	v_mfma_f32_16x16x32_bf16 v[94:97], v[134:137], v[190:193], v[94:97]
	v_mfma_f32_16x16x32_bf16 v[90:93], v[142:145], v[190:193], v[90:93]
	s_setprio 0
	s_setprio 1
	v_mfma_f32_16x16x32_bf16 v[22:25], v[146:149], v[162:165], v[22:25]
	v_mfma_f32_16x16x32_bf16 v[6:9], v[154:157], v[162:165], v[6:9]
	v_mfma_f32_16x16x32_bf16 v[18:21], v[146:149], v[170:173], v[18:21]
	v_mfma_f32_16x16x32_bf16 v[2:5], v[154:157], v[170:173], v[2:5]
	v_mfma_f32_16x16x32_bf16 v[86:89], v[146:149], v[178:181], v[86:89]
	v_mfma_f32_16x16x32_bf16 v[82:85], v[154:157], v[178:181], v[82:85]
	v_mfma_f32_16x16x32_bf16 v[78:81], v[146:149], v[186:189], v[78:81]
	v_mfma_f32_16x16x32_bf16 v[74:77], v[154:157], v[186:189], v[74:77]
	v_mfma_f32_16x16x32_bf16 v[22:25], v[150:153], v[166:169], v[22:25]
	v_mfma_f32_16x16x32_bf16 v[6:9], v[158:161], v[166:169], v[6:9]
	v_mfma_f32_16x16x32_bf16 v[18:21], v[150:153], v[174:177], v[18:21]
	v_mfma_f32_16x16x32_bf16 v[2:5], v[158:161], v[174:177], v[2:5]
	v_mfma_f32_16x16x32_bf16 v[86:89], v[150:153], v[182:185], v[86:89]
	v_mfma_f32_16x16x32_bf16 v[82:85], v[158:161], v[182:185], v[82:85]
	v_mfma_f32_16x16x32_bf16 v[78:81], v[150:153], v[190:193], v[78:81]
	s_barrier
	v_mfma_f32_16x16x32_bf16 v[74:77], v[158:161], v[190:193], v[74:77]
	s_setprio 0
	s_add_i32 s73, s73, 2
	s_add_u32 s59, s59, 0x100
	s_addc_u32 s72, s72, 0
	s_cmp_gt_u32 s73, 13
	s_mov_b64 s[42:43], s[38:39]
.LBB0_390:
	s_add_u32 s38, s42, 0x100
	s_addc_u32 s39, s43, 0
	s_add_i32 s4, 0, 0x10000
	s_cmp_eq_u32 s73, 12
	s_cselect_b32 s69, s29, s39
	s_cselect_b32 s68, vcc_lo, s38
	s_cselect_b32 s67, s37, s72
	s_cselect_b32 s66, vcc_hi, s59
	s_add_i32 s6, 0, 0x14000
	v_add_u32_e32 v142, s4, v251
	v_add_u32_e32 v158, s6, v251
	ds_read_b128 v[130:133], v142
	ds_read_b128 v[134:137], v142 offset:1024
	ds_read_b128 v[138:141], v142 offset:2048
	ds_read_b128 v[142:145], v142 offset:3072
	ds_read_b128 v[146:149], v158
	ds_read_b128 v[150:153], v158 offset:1024
	ds_read_b128 v[154:157], v158 offset:2048
	ds_read_b128 v[158:161], v158 offset:3072
	s_add_i32 m0, s75, 0xc000
	ds_read_b128 v[162:165], v244
	ds_read_b128 v[166:169], v244 offset:1024
	ds_read_b128 v[170:173], v244 offset:2048
	ds_read_b128 v[174:177], v244 offset:3072
	ds_read_b128 v[178:181], v244 offset:4096
	ds_read_b128 v[182:185], v244 offset:5120
	ds_read_b128 v[186:189], v244 offset:6144
	ds_read_b128 v[190:193], v244 offset:7168
	global_load_lds_dwordx4 v228, s[42:43]
	s_add_i32 m0, s75, 0xe000
	s_nop 0
	global_load_lds_dwordx4 v230, s[42:43]
	s_waitcnt vmcnt(8)
	s_waitcnt lgkmcnt(0)
	s_barrier
	s_setprio 1
	s_waitcnt lgkmcnt(0)
	v_mfma_f32_16x16x32_bf16 v[114:117], v[130:133], v[162:165], v[114:117]
	v_mfma_f32_16x16x32_bf16 v[122:125], v[138:141], v[162:165], v[122:125]
	v_mfma_f32_16x16x32_bf16 v[118:121], v[130:133], v[170:173], v[118:121]
	v_mfma_f32_16x16x32_bf16 v[126:129], v[138:141], v[170:173], v[126:129]
	v_mfma_f32_16x16x32_bf16 v[54:57], v[130:133], v[178:181], v[54:57]
	v_mfma_f32_16x16x32_bf16 v[70:73], v[138:141], v[178:181], v[70:73]
	v_mfma_f32_16x16x32_bf16 v[50:53], v[130:133], v[186:189], v[50:53]
	v_mfma_f32_16x16x32_bf16 v[66:69], v[138:141], v[186:189], v[66:69]
	v_mfma_f32_16x16x32_bf16 v[114:117], v[134:137], v[166:169], v[114:117]
	v_mfma_f32_16x16x32_bf16 v[122:125], v[142:145], v[166:169], v[122:125]
	v_mfma_f32_16x16x32_bf16 v[118:121], v[134:137], v[174:177], v[118:121]
	v_mfma_f32_16x16x32_bf16 v[126:129], v[142:145], v[174:177], v[126:129]
	v_mfma_f32_16x16x32_bf16 v[54:57], v[134:137], v[182:185], v[54:57]
	v_mfma_f32_16x16x32_bf16 v[70:73], v[142:145], v[182:185], v[70:73]
	v_mfma_f32_16x16x32_bf16 v[50:53], v[134:137], v[190:193], v[50:53]
	v_mfma_f32_16x16x32_bf16 v[66:69], v[142:145], v[190:193], v[66:69]
	s_setprio 0
	s_setprio 1
	v_mfma_f32_16x16x32_bf16 v[106:109], v[146:149], v[162:165], v[106:109]
	v_mfma_f32_16x16x32_bf16 v[42:45], v[154:157], v[162:165], v[42:45]
	v_mfma_f32_16x16x32_bf16 v[110:113], v[146:149], v[170:173], v[110:113]
	v_mfma_f32_16x16x32_bf16 v[46:49], v[154:157], v[170:173], v[46:49]
	v_mfma_f32_16x16x32_bf16 v[30:33], v[146:149], v[178:181], v[30:33]
	v_mfma_f32_16x16x32_bf16 v[14:17], v[154:157], v[178:181], v[14:17]
	v_mfma_f32_16x16x32_bf16 v[26:29], v[146:149], v[186:189], v[26:29]
	v_mfma_f32_16x16x32_bf16 v[10:13], v[154:157], v[186:189], v[10:13]
	v_mfma_f32_16x16x32_bf16 v[106:109], v[150:153], v[166:169], v[106:109]
	v_mfma_f32_16x16x32_bf16 v[42:45], v[158:161], v[166:169], v[42:45]
	v_mfma_f32_16x16x32_bf16 v[110:113], v[150:153], v[174:177], v[110:113]
	v_mfma_f32_16x16x32_bf16 v[46:49], v[158:161], v[174:177], v[46:49]
	v_mfma_f32_16x16x32_bf16 v[30:33], v[150:153], v[182:185], v[30:33]
	v_mfma_f32_16x16x32_bf16 v[14:17], v[158:161], v[182:185], v[14:17]
	v_mfma_f32_16x16x32_bf16 v[26:29], v[150:153], v[190:193], v[26:29]
	s_barrier
	v_mfma_f32_16x16x32_bf16 v[10:13], v[158:161], v[190:193], v[10:13]
	s_setprio 0
	s_add_i32 s4, s4, s74
	s_mov_b32 m0, s4
	ds_read_b128 v[162:165], v244 offset:16384
	ds_read_b128 v[166:169], v244 offset:17408
	ds_read_b128 v[170:173], v244 offset:18432
	ds_read_b128 v[174:177], v244 offset:19456
	ds_read_b128 v[178:181], v244 offset:20480
	ds_read_b128 v[182:185], v244 offset:21504
	ds_read_b128 v[186:189], v244 offset:22528
	ds_read_b128 v[190:193], v244 offset:23552
	global_load_lds_dwordx4 v0, s[66:67]
	s_add_i32 m0, s4, 0x2000
	s_add_u32 s4, s66, 0x40000
	s_addc_u32 s5, s67, 0
	s_add_i32 s6, s6, s74
	global_load_lds_dwordx4 v224, s[66:67]
	s_mov_b32 m0, s6
	s_nop 0
	global_load_lds_dwordx4 v0, s[4:5]
	s_add_i32 m0, s6, 0x2000
	s_nop 0
	global_load_lds_dwordx4 v224, s[4:5]
	s_mov_b32 m0, s75
	s_nop 0
	global_load_lds_dwordx4 v226, s[68:69]
	s_mov_b32 m0, s76
	s_nop 0
	global_load_lds_dwordx4 v222, s[68:69]
	s_waitcnt vmcnt(8)
	s_waitcnt lgkmcnt(0)
	s_barrier
	s_setprio 1
	s_waitcnt lgkmcnt(0)
	v_mfma_f32_16x16x32_bf16 v[38:41], v[130:133], v[162:165], v[38:41]
	v_mfma_f32_16x16x32_bf16 v[62:65], v[138:141], v[162:165], v[62:65]
	v_mfma_f32_16x16x32_bf16 v[34:37], v[130:133], v[170:173], v[34:37]
	v_mfma_f32_16x16x32_bf16 v[58:61], v[138:141], v[170:173], v[58:61]
	v_mfma_f32_16x16x32_bf16 v[102:105], v[130:133], v[178:181], v[102:105]
	v_mfma_f32_16x16x32_bf16 v[98:101], v[138:141], v[178:181], v[98:101]
	v_mfma_f32_16x16x32_bf16 v[94:97], v[130:133], v[186:189], v[94:97]
	v_mfma_f32_16x16x32_bf16 v[90:93], v[138:141], v[186:189], v[90:93]
	v_mfma_f32_16x16x32_bf16 v[38:41], v[134:137], v[166:169], v[38:41]
	v_mfma_f32_16x16x32_bf16 v[62:65], v[142:145], v[166:169], v[62:65]
	v_mfma_f32_16x16x32_bf16 v[34:37], v[134:137], v[174:177], v[34:37]
	v_mfma_f32_16x16x32_bf16 v[58:61], v[142:145], v[174:177], v[58:61]
	v_mfma_f32_16x16x32_bf16 v[102:105], v[134:137], v[182:185], v[102:105]
	v_mfma_f32_16x16x32_bf16 v[98:101], v[142:145], v[182:185], v[98:101]
	v_mfma_f32_16x16x32_bf16 v[94:97], v[134:137], v[190:193], v[94:97]
	v_mfma_f32_16x16x32_bf16 v[90:93], v[142:145], v[190:193], v[90:93]
	s_setprio 0
	s_setprio 1
	v_mfma_f32_16x16x32_bf16 v[22:25], v[146:149], v[162:165], v[22:25]
	v_mfma_f32_16x16x32_bf16 v[6:9], v[154:157], v[162:165], v[6:9]
	v_mfma_f32_16x16x32_bf16 v[18:21], v[146:149], v[170:173], v[18:21]
	v_mfma_f32_16x16x32_bf16 v[2:5], v[154:157], v[170:173], v[2:5]
	v_mfma_f32_16x16x32_bf16 v[86:89], v[146:149], v[178:181], v[86:89]
	v_mfma_f32_16x16x32_bf16 v[82:85], v[154:157], v[178:181], v[82:85]
	v_mfma_f32_16x16x32_bf16 v[78:81], v[146:149], v[186:189], v[78:81]
	v_mfma_f32_16x16x32_bf16 v[74:77], v[154:157], v[186:189], v[74:77]
	v_mfma_f32_16x16x32_bf16 v[22:25], v[150:153], v[166:169], v[22:25]
	v_mfma_f32_16x16x32_bf16 v[6:9], v[158:161], v[166:169], v[6:9]
	v_mfma_f32_16x16x32_bf16 v[18:21], v[150:153], v[174:177], v[18:21]
	v_mfma_f32_16x16x32_bf16 v[2:5], v[158:161], v[174:177], v[2:5]
	v_mfma_f32_16x16x32_bf16 v[86:89], v[150:153], v[182:185], v[86:89]
	v_mfma_f32_16x16x32_bf16 v[82:85], v[158:161], v[182:185], v[82:85]
	v_mfma_f32_16x16x32_bf16 v[78:81], v[150:153], v[190:193], v[78:81]
	s_barrier
	v_mfma_f32_16x16x32_bf16 v[74:77], v[158:161], v[190:193], v[74:77]
	s_setprio 0
	s_add_i32 s6, 0, 0x18000
	s_add_i32 s7, 0, 0x1c000
	v_add_u32_e32 v142, s6, v251
	v_add_u32_e32 v158, s7, v251
	ds_read_b128 v[130:133], v142
	ds_read_b128 v[134:137], v142 offset:1024
	ds_read_b128 v[138:141], v142 offset:2048
	ds_read_b128 v[142:145], v142 offset:3072
	ds_read_b128 v[146:149], v158
	ds_read_b128 v[150:153], v158 offset:1024
	ds_read_b128 v[154:157], v158 offset:2048
	ds_read_b128 v[158:161], v158 offset:3072
	s_add_u32 s4, s68, 0x2000
	s_addc_u32 s5, s69, 0
	s_mov_b32 m0, s77
	ds_read_b128 v[162:165], v244 offset:32768
	ds_read_b128 v[166:169], v244 offset:33792
	ds_read_b128 v[170:173], v244 offset:34816
	ds_read_b128 v[174:177], v244 offset:35840
	ds_read_b128 v[178:181], v244 offset:36864
	ds_read_b128 v[182:185], v244 offset:37888
	ds_read_b128 v[186:189], v244 offset:38912
	ds_read_b128 v[190:193], v244 offset:39936
	global_load_lds_dwordx4 v226, s[4:5]
	s_mov_b32 m0, s78
	s_nop 0
	global_load_lds_dwordx4 v222, s[4:5]
	s_waitcnt vmcnt(8)
	s_waitcnt lgkmcnt(0)
	s_barrier
	s_setprio 1
	s_waitcnt lgkmcnt(0)
	v_mfma_f32_16x16x32_bf16 v[114:117], v[130:133], v[162:165], v[114:117]
	v_mfma_f32_16x16x32_bf16 v[122:125], v[138:141], v[162:165], v[122:125]
	v_mfma_f32_16x16x32_bf16 v[118:121], v[130:133], v[170:173], v[118:121]
	v_mfma_f32_16x16x32_bf16 v[126:129], v[138:141], v[170:173], v[126:129]
	v_mfma_f32_16x16x32_bf16 v[54:57], v[130:133], v[178:181], v[54:57]
	v_mfma_f32_16x16x32_bf16 v[70:73], v[138:141], v[178:181], v[70:73]
	v_mfma_f32_16x16x32_bf16 v[50:53], v[130:133], v[186:189], v[50:53]
	v_mfma_f32_16x16x32_bf16 v[66:69], v[138:141], v[186:189], v[66:69]
	v_mfma_f32_16x16x32_bf16 v[114:117], v[134:137], v[166:169], v[114:117]
	v_mfma_f32_16x16x32_bf16 v[122:125], v[142:145], v[166:169], v[122:125]
	v_mfma_f32_16x16x32_bf16 v[118:121], v[134:137], v[174:177], v[118:121]
	v_mfma_f32_16x16x32_bf16 v[126:129], v[142:145], v[174:177], v[126:129]
	v_mfma_f32_16x16x32_bf16 v[54:57], v[134:137], v[182:185], v[54:57]
	v_mfma_f32_16x16x32_bf16 v[70:73], v[142:145], v[182:185], v[70:73]
	v_mfma_f32_16x16x32_bf16 v[50:53], v[134:137], v[190:193], v[50:53]
	v_mfma_f32_16x16x32_bf16 v[66:69], v[142:145], v[190:193], v[66:69]
	s_setprio 0
	s_setprio 1
	v_mfma_f32_16x16x32_bf16 v[106:109], v[146:149], v[162:165], v[106:109]
	v_mfma_f32_16x16x32_bf16 v[42:45], v[154:157], v[162:165], v[42:45]
	v_mfma_f32_16x16x32_bf16 v[110:113], v[146:149], v[170:173], v[110:113]
	v_mfma_f32_16x16x32_bf16 v[46:49], v[154:157], v[170:173], v[46:49]
	v_mfma_f32_16x16x32_bf16 v[30:33], v[146:149], v[178:181], v[30:33]
	v_mfma_f32_16x16x32_bf16 v[14:17], v[154:157], v[178:181], v[14:17]
	v_mfma_f32_16x16x32_bf16 v[26:29], v[146:149], v[186:189], v[26:29]
	v_mfma_f32_16x16x32_bf16 v[10:13], v[154:157], v[186:189], v[10:13]
	v_mfma_f32_16x16x32_bf16 v[106:109], v[150:153], v[166:169], v[106:109]
	v_mfma_f32_16x16x32_bf16 v[42:45], v[158:161], v[166:169], v[42:45]
	v_mfma_f32_16x16x32_bf16 v[110:113], v[150:153], v[174:177], v[110:113]
	v_mfma_f32_16x16x32_bf16 v[46:49], v[158:161], v[174:177], v[46:49]
	v_mfma_f32_16x16x32_bf16 v[30:33], v[150:153], v[182:185], v[30:33]
	v_mfma_f32_16x16x32_bf16 v[14:17], v[158:161], v[182:185], v[14:17]
	v_mfma_f32_16x16x32_bf16 v[26:29], v[150:153], v[190:193], v[26:29]
	s_barrier
	v_mfma_f32_16x16x32_bf16 v[10:13], v[158:161], v[190:193], v[10:13]
	s_setprio 0
	s_add_i32 s4, s6, s74
	s_mov_b32 m0, s4
	ds_read_b128 v[162:165], v244 offset:49152
	ds_read_b128 v[166:169], v244 offset:50176
	ds_read_b128 v[170:173], v244 offset:51200
	ds_read_b128 v[174:177], v244 offset:52224
	ds_read_b128 v[178:181], v244 offset:53248
	ds_read_b128 v[182:185], v244 offset:54272
	ds_read_b128 v[186:189], v244 offset:55296
	ds_read_b128 v[190:193], v244 offset:56320
	s_add_u32 s100, s66, 0x80
	s_addc_u32 s101, s67, 0
	global_load_lds_dwordx4 v0, s[100:101]
	s_add_i32 m0, s4, 0x2000
	s_add_u32 s4, s66, 0x40080
	s_addc_u32 s5, s67, 0
	s_add_i32 s6, s7, s74
	global_load_lds_dwordx4 v224, s[100:101]
	s_mov_b32 m0, s6
	s_nop 0
	global_load_lds_dwordx4 v0, s[4:5]
	s_add_i32 m0, s6, 0x2000
	s_nop 0
	global_load_lds_dwordx4 v224, s[4:5]
	s_mov_b32 m0, s94
	s_nop 0
	s_add_u32 s100, s68, 0x80
	s_addc_u32 s101, s69, 0
	global_load_lds_dwordx4 v226, s[100:101]
	s_mov_b32 m0, s95
	s_nop 0
	global_load_lds_dwordx4 v222, s[100:101]
	s_waitcnt vmcnt(8)
	s_waitcnt lgkmcnt(0)
	s_barrier
	s_setprio 1
	s_waitcnt lgkmcnt(0)
	v_mfma_f32_16x16x32_bf16 v[38:41], v[130:133], v[162:165], v[38:41]
	v_mfma_f32_16x16x32_bf16 v[62:65], v[138:141], v[162:165], v[62:65]
	v_mfma_f32_16x16x32_bf16 v[34:37], v[130:133], v[170:173], v[34:37]
	v_mfma_f32_16x16x32_bf16 v[58:61], v[138:141], v[170:173], v[58:61]
	v_mfma_f32_16x16x32_bf16 v[102:105], v[130:133], v[178:181], v[102:105]
	v_mfma_f32_16x16x32_bf16 v[98:101], v[138:141], v[178:181], v[98:101]
	v_mfma_f32_16x16x32_bf16 v[94:97], v[130:133], v[186:189], v[94:97]
	v_mfma_f32_16x16x32_bf16 v[90:93], v[138:141], v[186:189], v[90:93]
	v_mfma_f32_16x16x32_bf16 v[38:41], v[134:137], v[166:169], v[38:41]
	v_mfma_f32_16x16x32_bf16 v[62:65], v[142:145], v[166:169], v[62:65]
	v_mfma_f32_16x16x32_bf16 v[34:37], v[134:137], v[174:177], v[34:37]
	v_mfma_f32_16x16x32_bf16 v[58:61], v[142:145], v[174:177], v[58:61]
	v_mfma_f32_16x16x32_bf16 v[102:105], v[134:137], v[182:185], v[102:105]
	v_mfma_f32_16x16x32_bf16 v[98:101], v[142:145], v[182:185], v[98:101]
	v_mfma_f32_16x16x32_bf16 v[94:97], v[134:137], v[190:193], v[94:97]
	v_mfma_f32_16x16x32_bf16 v[90:93], v[142:145], v[190:193], v[90:93]
	s_setprio 0
	s_setprio 1
	v_mfma_f32_16x16x32_bf16 v[22:25], v[146:149], v[162:165], v[22:25]
	v_mfma_f32_16x16x32_bf16 v[6:9], v[154:157], v[162:165], v[6:9]
	v_mfma_f32_16x16x32_bf16 v[18:21], v[146:149], v[170:173], v[18:21]
	v_mfma_f32_16x16x32_bf16 v[2:5], v[154:157], v[170:173], v[2:5]
	v_mfma_f32_16x16x32_bf16 v[86:89], v[146:149], v[178:181], v[86:89]
	v_mfma_f32_16x16x32_bf16 v[82:85], v[154:157], v[178:181], v[82:85]
	v_mfma_f32_16x16x32_bf16 v[78:81], v[146:149], v[186:189], v[78:81]
	v_mfma_f32_16x16x32_bf16 v[74:77], v[154:157], v[186:189], v[74:77]
	v_mfma_f32_16x16x32_bf16 v[22:25], v[150:153], v[166:169], v[22:25]
	v_mfma_f32_16x16x32_bf16 v[6:9], v[158:161], v[166:169], v[6:9]
	v_mfma_f32_16x16x32_bf16 v[18:21], v[150:153], v[174:177], v[18:21]
	v_mfma_f32_16x16x32_bf16 v[2:5], v[158:161], v[174:177], v[2:5]
	v_mfma_f32_16x16x32_bf16 v[86:89], v[150:153], v[182:185], v[86:89]
	v_mfma_f32_16x16x32_bf16 v[82:85], v[158:161], v[182:185], v[82:85]
	v_mfma_f32_16x16x32_bf16 v[78:81], v[150:153], v[190:193], v[78:81]
	s_barrier
	v_mfma_f32_16x16x32_bf16 v[74:77], v[158:161], v[190:193], v[74:77]
	s_setprio 0
	s_add_i32 s73, s73, 2
	s_add_u32 s59, s59, 0x100
	s_addc_u32 s72, s72, 0
	s_cmp_gt_u32 s73, 13
	s_mov_b64 s[42:43], s[38:39]
	s_cbranch_scc0 .LBB0_390
	s_and_b64 vcc, exec, s[50:51]
	s_cbranch_vccz .LBB0_393
	s_barrier
